# P7 fused epilogue: norm_f loads issued at the epilogue start into free registers (moved out of the tail's last round trip)
# baseline (speedup 1.0000x reference)
; #define PG8_LAS __attribute__((address_space(3)))
;     __device__ __forceinline__ void fused(f32x4 (&acc)[2][2][4][2], const Unit& u, int wr, int wc, int fr, int fq, PG8_LAS unsigned char* lds, int wid, int lane) const {
;         if (u.nt != FF / BK) { (*this)(acc, u, wr, wc, fr, fq); return; }
;         PG8_LAS float* Pp = (PG8_LAS float*)(lds + 131072 + 1024); PG8_LAS float* Sr = (PG8_LAS float*)(lds + 131072 + 1024 + 4096);
;         const int tid = wid * 64 + lane;
; #pragma unroll
;         for (int j = 0; j < 16; ++j) {
;             const int rA = wid * 32 + 2 * j, rl = rA + (lane >> 5), chunk = ((lane & 31) + rl) & 31;
;             const bf16_t* src = h1b + (size_t)(u.pm * BM + rl) * DM + u.pn * BM + chunk * 8;
;             __builtin_amdgcn_global_load_lds((const unsigned*)src, (PG8_LAS unsigned*)(lds + rA * 512), 16, 0, 2);
;     ...
;         f32x4 nf[2][2];
; #pragma unroll
;         for (int bj = 0; bj < 2; ++bj)
; #pragma unroll
;             for (int n = 0; n < 2; ++n) nf[bj][n] = *(const f32x4*)(normf + u.pn * BM + wc * 64 + bj * 32 + n * 4 + 8 * fq);
.LBB0_1063:
	s_lshl_b64 s[98:99], s[2:3], 2
	s_add_u32 s98, s60, s98
	s_addc_u32 s99, s61, s99
	s_lshl_b32 s101, s46, 2
	s_add_u32 s98, s98, s101
	s_addc_u32 s99, s99, 0
	v_lshlrev_b32_e32 v228, 2, v132
	global_load_dwordx4 v[212:215], v228, s[98:99]
	global_load_dwordx4 v[216:219], v228, s[98:99] offset:16
	global_load_dwordx4 v[220:223], v228, s[98:99] offset:128
	global_load_dwordx4 v[224:227], v228, s[98:99] offset:144
	s_andn2_b64 vcc, exec, s[4:5]
	s_cbranch_vccnz .LBB0_1102
	v_lshrrev_b32_e32 v134, 5, v133
	v_or_b32_e32 v128, s65, v134
	s_lshl_b32 s16, s12, 8
	v_add_u32_e32 v128, s16, v128
	v_ashrrev_i32_e32 v129, 31, v128
	v_lshlrev_b64 v[128:129], 11, v[128:129]
	v_lshl_add_u64 v[128:129], s[8:9], 0, v[128:129]
	s_lshl_b64 s[0:1], s[2:3], 1
	v_readlane_b32 s4, v255, 13
	v_lshl_add_u64 v[130:131], v[128:129], 0, s[0:1]
	v_add_lshl_u32 v128, v134, v133, 4
	s_lshl_b32 s4, s4, 14
	v_and_b32_e32 v128, 0x1f0, v128
	v_mov_b32_e32 v129, 0
	s_add_i32 m0, s4, 0
	s_or_b32 s4, s65, 2
	v_lshl_add_u64 v[130:131], v[130:131], 0, v[128:129]
	v_or_b32_e32 v128, s4, v134
	global_load_lds_dwordx4 v[130:131], off nt
	v_add_u32_e32 v130, s16, v128
	v_ashrrev_i32_e32 v131, 31, v130
	v_lshlrev_b64 v[130:131], 11, v[130:131]
	v_lshl_add_u64 v[130:131], s[8:9], 0, v[130:131]
	v_add_lshl_u32 v128, v128, v153, 4
	s_lshl_b32 s4, s4, 9
	v_lshl_add_u64 v[130:131], v[130:131], 0, s[0:1]
	v_and_b32_e32 v128, 0x1f0, v128
	s_add_i32 m0, s4, 0
	s_or_b32 s4, s65, 4
	v_lshl_add_u64 v[130:131], v[130:131], 0, v[128:129]
	v_or_b32_e32 v128, s4, v134
	global_load_lds_dwordx4 v[130:131], off nt
	v_add_u32_e32 v130, s16, v128
	v_ashrrev_i32_e32 v131, 31, v130
	v_lshlrev_b64 v[130:131], 11, v[130:131]
	v_lshl_add_u64 v[130:131], s[8:9], 0, v[130:131]
	v_add_lshl_u32 v128, v128, v153, 4
	s_lshl_b32 s4, s4, 9
	v_lshl_add_u64 v[130:131], v[130:131], 0, s[0:1]
	v_and_b32_e32 v128, 0x1f0, v128
	s_add_i32 m0, s4, 0
	s_or_b32 s4, s65, 6
	v_lshl_add_u64 v[130:131], v[130:131], 0, v[128:129]
	v_or_b32_e32 v128, s4, v134
	global_load_lds_dwordx4 v[130:131], off nt
	v_add_u32_e32 v130, s16, v128
	v_ashrrev_i32_e32 v131, 31, v130
	v_lshlrev_b64 v[130:131], 11, v[130:131]
	v_lshl_add_u64 v[130:131], s[8:9], 0, v[130:131]
	v_add_lshl_u32 v128, v128, v153, 4
	s_lshl_b32 s4, s4, 9
	v_lshl_add_u64 v[130:131], v[130:131], 0, s[0:1]
	v_and_b32_e32 v128, 0x1f0, v128
	s_add_i32 m0, s4, 0
	s_or_b32 s4, s65, 8
	v_lshl_add_u64 v[130:131], v[130:131], 0, v[128:129]
	v_or_b32_e32 v128, s4, v134
	global_load_lds_dwordx4 v[130:131], off nt
	v_add_u32_e32 v130, s16, v128
	v_ashrrev_i32_e32 v131, 31, v130
	v_lshlrev_b64 v[130:131], 11, v[130:131]
	v_lshl_add_u64 v[130:131], s[8:9], 0, v[130:131]
	v_add_lshl_u32 v128, v128, v153, 4
	s_lshl_b32 s4, s4, 9
	v_lshl_add_u64 v[130:131], v[130:131], 0, s[0:1]
	v_and_b32_e32 v128, 0x1f0, v128
	s_add_i32 m0, s4, 0
	s_or_b32 s4, s65, 10
	v_lshl_add_u64 v[130:131], v[130:131], 0, v[128:129]
	v_or_b32_e32 v128, s4, v134
	global_load_lds_dwordx4 v[130:131], off nt
	v_add_u32_e32 v130, s16, v128
	v_ashrrev_i32_e32 v131, 31, v130
	v_lshlrev_b64 v[130:131], 11, v[130:131]
	v_lshl_add_u64 v[130:131], s[8:9], 0, v[130:131]
	v_add_lshl_u32 v128, v128, v153, 4
	s_lshl_b32 s4, s4, 9
	v_lshl_add_u64 v[130:131], v[130:131], 0, s[0:1]
	v_and_b32_e32 v128, 0x1f0, v128
	s_add_i32 m0, s4, 0
	s_or_b32 s4, s65, 12
	v_lshl_add_u64 v[130:131], v[130:131], 0, v[128:129]
	v_or_b32_e32 v128, s4, v134
	global_load_lds_dwordx4 v[130:131], off nt
	v_add_u32_e32 v130, s16, v128
	v_ashrrev_i32_e32 v131, 31, v130
	v_lshlrev_b64 v[130:131], 11, v[130:131]
	v_lshl_add_u64 v[130:131], s[8:9], 0, v[130:131]
	v_add_lshl_u32 v128, v128, v153, 4
	s_lshl_b32 s4, s4, 9
	v_lshl_add_u64 v[130:131], v[130:131], 0, s[0:1]
	v_and_b32_e32 v128, 0x1f0, v128
	s_add_i32 m0, s4, 0
	s_or_b32 s4, s65, 14
	v_lshl_add_u64 v[130:131], v[130:131], 0, v[128:129]
	v_or_b32_e32 v128, s4, v134
	global_load_lds_dwordx4 v[130:131], off nt
	v_add_u32_e32 v130, s16, v128
	v_ashrrev_i32_e32 v131, 31, v130
	v_lshlrev_b64 v[130:131], 11, v[130:131]
	v_lshl_add_u64 v[130:131], s[8:9], 0, v[130:131]
	v_add_lshl_u32 v128, v128, v153, 4
	s_lshl_b32 s4, s4, 9
	v_lshl_add_u64 v[130:131], v[130:131], 0, s[0:1]
	v_and_b32_e32 v128, 0x1f0, v128
	s_add_i32 m0, s4, 0
	s_or_b32 s4, s65, 16
	v_lshl_add_u64 v[130:131], v[130:131], 0, v[128:129]
	v_or_b32_e32 v128, s4, v134
	global_load_lds_dwordx4 v[130:131], off nt
	v_add_u32_e32 v130, s16, v128
	v_ashrrev_i32_e32 v131, 31, v130
	v_lshlrev_b64 v[130:131], 11, v[130:131]
	v_lshl_add_u64 v[130:131], s[8:9], 0, v[130:131]
	v_add_lshl_u32 v128, v128, v153, 4
	s_lshl_b32 s4, s4, 9
	v_lshl_add_u64 v[130:131], v[130:131], 0, s[0:1]
	v_and_b32_e32 v128, 0x1f0, v128
	s_add_i32 m0, s4, 0
	s_or_b32 s4, s65, 18
	v_lshl_add_u64 v[130:131], v[130:131], 0, v[128:129]
	v_or_b32_e32 v128, s4, v134
	global_load_lds_dwordx4 v[130:131], off nt
	v_add_u32_e32 v130, s16, v128
	v_ashrrev_i32_e32 v131, 31, v130
	v_lshlrev_b64 v[130:131], 11, v[130:131]
	v_lshl_add_u64 v[130:131], s[8:9], 0, v[130:131]
	v_add_lshl_u32 v128, v128, v153, 4
	s_lshl_b32 s4, s4, 9
	v_lshl_add_u64 v[130:131], v[130:131], 0, s[0:1]
	v_and_b32_e32 v128, 0x1f0, v128
	s_add_i32 m0, s4, 0
	s_or_b32 s4, s65, 20
	v_lshl_add_u64 v[130:131], v[130:131], 0, v[128:129]
	v_or_b32_e32 v128, s4, v134
	global_load_lds_dwordx4 v[130:131], off nt
	v_add_u32_e32 v130, s16, v128
	v_ashrrev_i32_e32 v131, 31, v130
	v_lshlrev_b64 v[130:131], 11, v[130:131]
; DI float bflo(unsigned u) { return __uint_as_float(u << 16); }
; DI float bfhi(unsigned u) { return __uint_as_float(u & 0xffff0000u); }
; #define PG8_LAS __attribute__((address_space(3)))
;     __device__ __forceinline__ void fused(f32x4 (&acc)[2][2][4][2], const Unit& u, int wr, int wc, int fr, int fq, PG8_LAS unsigned char* lds, int wid, int lane) const {
;     ...
;         for (int j = 0; j < 16; ++j) {
;             const int rA = wid * 32 + 2 * j, rl = rA + (lane >> 5), chunk = ((lane & 31) + rl) & 31;
;             const bf16_t* src = h1b + (size_t)(u.pm * BM + rl) * DM + u.pn * BM + chunk * 8;
;             __builtin_amdgcn_global_load_lds((const unsigned*)src, (PG8_LAS unsigned*)(lds + rA * 512), 16, 0, 2);
;         }
;         asm volatile("s_waitcnt vmcnt(0)" ::: "memory"); __builtin_amdgcn_s_barrier(); asm volatile("" ::: "memory");
; #pragma unroll
;         for (int ai = 0; ai < 2; ++ai)
; #pragma unroll
;             for (int m = 0; m < 4; ++m) {
;                 const int rl = ai * HALF + wr * 64 + m * 16 + fr;
;                 float ss = 0.f;
; #pragma unroll
;                 for (int bj = 0; bj < 2; ++bj) {
;                     const int pos = (wc * 8 + bj * 4 + fq - rl) & 31;
;                     const u32x4 xb = *(const PG8_LAS u32x4*)(lds + rl * 512 + pos * 16);
;                     const f32x4 h0 = acc[ai][bj][m][0] + (f32x4){bflo(xb.x), bfhi(xb.x), bflo(xb.y), bfhi(xb.y)}, h1 = acc[ai][bj][m][1] + (f32x4){bflo(xb.z), bfhi(xb.z), bflo(xb.w), bfhi(xb.w)};
;                     acc[ai][bj][m][0] = h0; acc[ai][bj][m][1] = h1;
;                     ss += ((h0[0] * h0[0] + h0[1] * h0[1]) + (h0[2] * h0[2] + h0[3] * h0[3])) + ((h1[0] * h1[0] + h1[1] * h1[1]) + (h1[2] * h1[2] + h1[3] * h1[3]));
;                 }
;                 ss += __shfl_xor(ss, 16); ss += __shfl_xor(ss, 32);
;                 if (fq == 0) Pp[rl * 4 + wc] = ss;
	v_lshl_add_u64 v[130:131], s[8:9], 0, v[130:131]
	v_add_lshl_u32 v128, v128, v153, 4
	s_lshl_b32 s4, s4, 9
	v_lshl_add_u64 v[130:131], v[130:131], 0, s[0:1]
	v_and_b32_e32 v128, 0x1f0, v128
	s_add_i32 m0, s4, 0
	s_or_b32 s4, s65, 22
	v_lshl_add_u64 v[130:131], v[130:131], 0, v[128:129]
	v_or_b32_e32 v128, s4, v134
	global_load_lds_dwordx4 v[130:131], off nt
	v_add_u32_e32 v130, s16, v128
	v_ashrrev_i32_e32 v131, 31, v130
	v_lshlrev_b64 v[130:131], 11, v[130:131]
	v_lshl_add_u64 v[130:131], s[8:9], 0, v[130:131]
	v_add_lshl_u32 v128, v128, v153, 4
	s_lshl_b32 s4, s4, 9
	v_lshl_add_u64 v[130:131], v[130:131], 0, s[0:1]
	v_and_b32_e32 v128, 0x1f0, v128
	s_add_i32 m0, s4, 0
	s_or_b32 s4, s65, 24
	v_lshl_add_u64 v[130:131], v[130:131], 0, v[128:129]
	v_or_b32_e32 v128, s4, v134
	global_load_lds_dwordx4 v[130:131], off nt
	v_add_u32_e32 v130, s16, v128
	v_ashrrev_i32_e32 v131, 31, v130
	v_lshlrev_b64 v[130:131], 11, v[130:131]
	v_lshl_add_u64 v[130:131], s[8:9], 0, v[130:131]
	v_add_lshl_u32 v128, v128, v153, 4
	s_lshl_b32 s4, s4, 9
	v_lshl_add_u64 v[130:131], v[130:131], 0, s[0:1]
	v_and_b32_e32 v128, 0x1f0, v128
	s_add_i32 m0, s4, 0
	s_or_b32 s4, s65, 26
	v_lshl_add_u64 v[130:131], v[130:131], 0, v[128:129]
	v_or_b32_e32 v128, s4, v134
	global_load_lds_dwordx4 v[130:131], off nt
	v_add_u32_e32 v130, s16, v128
	v_ashrrev_i32_e32 v131, 31, v130
	v_lshlrev_b64 v[130:131], 11, v[130:131]
	v_lshl_add_u64 v[130:131], s[8:9], 0, v[130:131]
	v_add_lshl_u32 v128, v128, v153, 4
	s_lshl_b32 s4, s4, 9
	v_lshl_add_u64 v[130:131], v[130:131], 0, s[0:1]
	v_and_b32_e32 v128, 0x1f0, v128
	s_add_i32 m0, s4, 0
	s_or_b32 s4, s65, 28
	v_lshl_add_u64 v[130:131], v[130:131], 0, v[128:129]
	v_or_b32_e32 v128, s4, v134
	global_load_lds_dwordx4 v[130:131], off nt
	v_add_u32_e32 v130, s16, v128
	v_ashrrev_i32_e32 v131, 31, v130
	v_lshlrev_b64 v[130:131], 11, v[130:131]
	v_lshl_add_u64 v[130:131], s[8:9], 0, v[130:131]
	v_add_lshl_u32 v128, v128, v153, 4
	s_lshl_b32 s4, s4, 9
	v_lshl_add_u64 v[130:131], v[130:131], 0, s[0:1]
	v_and_b32_e32 v128, 0x1f0, v128
	s_add_i32 m0, s4, 0
	s_or_b32 s4, s65, 30
	v_lshl_add_u64 v[130:131], v[130:131], 0, v[128:129]
	v_or_b32_e32 v128, s4, v134
	global_load_lds_dwordx4 v[130:131], off nt
	v_add_u32_e32 v130, s16, v128
	v_ashrrev_i32_e32 v131, 31, v130
	v_lshlrev_b64 v[130:131], 11, v[130:131]
	v_lshl_add_u64 v[130:131], s[8:9], 0, v[130:131]
	v_add_lshl_u32 v128, v128, v153, 4
	v_lshl_add_u64 v[130:131], v[130:131], 0, s[0:1]
	v_and_b32_e32 v128, 0x1f0, v128
	s_lshl_b32 s0, s4, 9
	v_lshl_add_u64 v[128:129], v[130:131], 0, v[128:129]
	s_add_i32 m0, s0, 0
	v_lshl_add_u32 v131, v152, 9, 0
	global_load_lds_dwordx4 v[128:129], off nt
	v_and_b32_e32 v129, 64, v201
	v_add_u32_e32 v129, 64, v129
	v_cmp_lt_i32_e32 vcc, v209, v129
	v_lshl_or_b32 v128, s48, 3, v154
	s_waitcnt vmcnt(0)
	s_barrier
	v_cndmask_b32_e32 v130, v201, v209, vcc
	v_lshlrev_b32_e32 v146, 2, v130
	v_sub_u32_e32 v130, v128, v152
	v_lshlrev_b32_e32 v130, 4, v130
	v_and_b32_e32 v134, 0x1f0, v130
	v_add_u32_e32 v134, v131, v134
	ds_read_b128 v[134:137], v134
	v_add_u32_e32 v130, 64, v130
	v_and_b32_e32 v130, 0x1f0, v130
	v_add_u32_e32 v130, v131, v130
	ds_read_b128 v[138:141], v130
	s_waitcnt lgkmcnt(0)
	v_lshlrev_b32_e32 v130, 16, v134
	v_and_b32_e32 v131, 0xffff0000, v134
	v_lshlrev_b32_e32 v134, 16, v135
	v_and_b32_e32 v135, 0xffff0000, v135
	v_pk_add_f32 v[126:127], v[126:127], v[134:135]
	v_pk_add_f32 v[124:125], v[124:125], v[130:131]
	v_lshlrev_b32_e32 v130, 16, v136
	v_and_b32_e32 v131, 0xffff0000, v136
	v_lshlrev_b32_e32 v134, 16, v137
	v_and_b32_e32 v135, 0xffff0000, v137
	v_pk_add_f32 v[120:121], v[120:121], v[130:131]
	v_mul_f32_e32 v130, v125, v125
	v_mul_f32_e32 v131, v127, v127
	v_pk_add_f32 v[122:123], v[122:123], v[134:135]
	v_fmac_f32_e32 v130, v124, v124
	v_fmac_f32_e32 v131, v126, v126
	v_add_f32_e32 v130, v130, v131
	v_mul_f32_e32 v131, v121, v121
	v_mul_f32_e32 v134, v123, v123
	v_fmac_f32_e32 v131, v120, v120
	v_fmac_f32_e32 v134, v122, v122
	v_add_f32_e32 v131, v131, v134
	v_add_f32_e32 v136, v130, v131
	v_lshlrev_b32_e32 v130, 16, v138
	v_and_b32_e32 v131, 0xffff0000, v138
	v_lshlrev_b32_e32 v134, 16, v139
	v_and_b32_e32 v135, 0xffff0000, v139
	v_pk_add_f32 v[118:119], v[118:119], v[134:135]
	v_pk_add_f32 v[116:117], v[116:117], v[130:131]
	v_lshlrev_b32_e32 v130, 16, v140
	v_and_b32_e32 v131, 0xffff0000, v140
	v_lshlrev_b32_e32 v134, 16, v141
	v_and_b32_e32 v135, 0xffff0000, v141
	v_pk_add_f32 v[112:113], v[112:113], v[130:131]
	v_mul_f32_e32 v130, v117, v117
	v_mul_f32_e32 v131, v119, v119
	v_pk_add_f32 v[114:115], v[114:115], v[134:135]
	v_fmac_f32_e32 v130, v116, v116
	v_fmac_f32_e32 v131, v118, v118
	v_add_f32_e32 v130, v130, v131
	v_mul_f32_e32 v131, v113, v113
	v_mul_f32_e32 v134, v115, v115
	v_fmac_f32_e32 v131, v112, v112
	v_fmac_f32_e32 v134, v114, v114
	v_add_f32_e32 v131, v131, v134
	v_add_f32_e32 v130, v130, v131
	v_add_f32_e32 v130, v136, v130
	ds_bpermute_b32 v131, v146, v130
	v_cmp_lt_i32_e32 vcc, v254, v129
	s_lshl_b32 s0, s48, 2
	s_add_i32 s4, s0, 0
	v_cndmask_b32_e32 v129, v201, v254, vcc
	v_lshlrev_b32_e32 v147, 2, v129
	s_waitcnt lgkmcnt(0)
	v_add_f32_e32 v129, v130, v131
	ds_bpermute_b32 v130, v147, v129
	v_cmp_gt_u32_e32 vcc, 16, v133
	s_add_i32 s4, s4, 0x20400
	s_and_saveexec_b64 s[0:1], vcc
	s_cbranch_execz .LBB0_1066
	v_lshl_add_u32 v131, v152, 4, s4
	s_waitcnt lgkmcnt(0)
	v_add_f32_e32 v129, v129, v130
	ds_write_b32 v131, v129

;     __device__ __forceinline__ void fused(f32x4 (&acc)[2][2][4][2], const Unit& u, int wr, int wc, int fr, int fq, PG8_LAS unsigned char* lds, int wid, int lane) const {
;     ...
;         f32x4 nf[2][2];
; #pragma unroll
;         for (int bj = 0; bj < 2; ++bj)
; #pragma unroll
;             for (int n = 0; n < 2; ++n) nf[bj][n] = *(const f32x4*)(normf + u.pn * BM + wc * 64 + bj * 32 + n * 4 + 8 * fq);
; #pragma unroll
;         for (int ai = 0; ai < 2; ++ai)
; #pragma unroll
;             for (int m = 0; m < 4; ++m) {
;                 const int rl = ai * HALF + wr * 64 + m * 16 + fr; const size_t row = (size_t)(u.pm * BM + rl);
;                 const float rs = Sr[rl];
; #pragma unroll
;                 for (int bj = 0; bj < 2; ++bj)
; #pragma unroll
;                     for (int n = 0; n < 2; ++n)
;                         *(f32x4*)(y + row * DM + u.pn * BM + wc * 64 + bj * 32 + n * 4 + 8 * fq) = acc[ai][bj][m][n] * rs * nf[bj][n];
.LBB0_1101:
	s_or_b64 exec, exec, s[8:9]
	s_lshl_b64 s[0:1], s[2:3], 2
	s_add_u32 s3, s60, s0
	s_addc_u32 s5, s61, s1
	s_lshl_b32 s2, s46, 2
	s_add_u32 s4, s3, s2
	s_waitcnt lgkmcnt(0)
	s_barrier
	s_addc_u32 s5, s5, 0
	v_lshlrev_b32_e32 v132, 2, v132
	v_mov_b32_e32 v12, v212
	v_mov_b32_e32 v13, v213
	v_mov_b32_e32 v14, v214
	v_mov_b32_e32 v15, v215
	v_mov_b32_e32 v8, v216
	v_mov_b32_e32 v9, v217
	v_mov_b32_e32 v10, v218
	v_mov_b32_e32 v11, v219
	v_mov_b32_e32 v4, v220
	v_mov_b32_e32 v5, v221
	v_mov_b32_e32 v6, v222
	v_mov_b32_e32 v7, v223
	v_mov_b32_e32 v0, v224
	v_mov_b32_e32 v1, v225
	v_mov_b32_e32 v2, v226
	v_mov_b32_e32 v3, v227
	s_add_i32 s4, 0, 0x21400
	v_lshl_add_u32 v161, v152, 2, s4
	v_add_u32_e32 v146, s16, v152
	v_add_u32_e32 v154, s16, v148
	v_add_u32_e32 v156, s16, v149
	v_lshl_add_u32 v150, v148, 2, s4
	v_lshl_add_u32 v152, v149, 2, s4
	ds_read2st64_b32 v[148:149], v161 offset1:2
	v_ashrrev_i32_e32 v147, 31, v146
	v_ashrrev_i32_e32 v155, 31, v154
	v_ashrrev_i32_e32 v157, 31, v156
	v_lshlrev_b64 v[162:163], 12, v[146:147]
	v_lshlrev_b64 v[154:155], 12, v[154:155]
	v_lshlrev_b64 v[146:147], 12, v[156:157]
	v_lshl_add_u64 v[156:157], s[62:63], 0, v[162:163]
	v_lshl_add_u32 v163, v151, 2, s4
	ds_read_b32 v162, v150
	ds_read_b32 v152, v152
	ds_read_b32 v150, v163
	ds_read_b32 v164, v161 offset:704
	s_mov_b32 s3, 0
	v_lshl_add_u64 v[154:155], s[62:63], 0, v[154:155]
	v_lshl_add_u64 v[156:157], v[156:157], 0, s[0:1]
	v_mov_b32_e32 v133, 0
	v_lshl_add_u64 v[154:155], v[154:155], 0, s[0:1]
	v_lshl_add_u64 v[156:157], v[156:157], 0, s[2:3]
	s_waitcnt lgkmcnt(0)
	v_pk_mul_f32 v[126:127], v[126:127], v[148:149] op_sel_hi:[1,0]
	v_pk_mul_f32 v[124:125], v[124:125], v[148:149] op_sel_hi:[1,0]
	v_lshl_add_u64 v[154:155], v[154:155], 0, s[2:3]
	v_lshl_add_u64 v[156:157], v[156:157], 0, v[132:133]
	v_pk_mul_f32 v[122:123], v[122:123], v[148:149] op_sel_hi:[1,0]
	v_pk_mul_f32 v[120:121], v[120:121], v[148:149] op_sel_hi:[1,0]
	v_pk_mul_f32 v[118:119], v[118:119], v[148:149] op_sel_hi:[1,0]
	v_pk_mul_f32 v[116:117], v[116:117], v[148:149] op_sel_hi:[1,0]
	v_pk_mul_f32 v[114:115], v[114:115], v[148:149] op_sel_hi:[1,0]
	v_pk_mul_f32 v[112:113], v[112:113], v[148:149] op_sel_hi:[1,0]
	v_pk_mul_f32 v[110:111], v[110:111], v[162:163] op_sel_hi:[1,0]
	v_pk_mul_f32 v[108:109], v[108:109], v[162:163] op_sel_hi:[1,0]
	v_pk_mul_f32 v[166:167], v[106:107], v[162:163] op_sel_hi:[1,0]
	v_pk_mul_f32 v[168:169], v[104:105], v[162:163] op_sel_hi:[1,0]
	v_pk_mul_f32 v[170:171], v[102:103], v[162:163] op_sel_hi:[1,0]
	v_pk_mul_f32 v[172:173], v[100:101], v[162:163] op_sel_hi:[1,0]
	v_pk_mul_f32 v[176:177], v[98:99], v[162:163] op_sel_hi:[1,0]
	v_pk_mul_f32 v[162:163], v[96:97], v[162:163] op_sel_hi:[1,0]
	v_pk_mul_f32 v[178:179], v[94:95], v[152:153] op_sel_hi:[1,0]
	v_pk_mul_f32 v[180:181], v[92:93], v[152:153] op_sel_hi:[1,0]
	v_lshl_add_u64 v[154:155], v[154:155], 0, v[132:133]
	v_pk_mul_f32 v[82:83], v[82:83], v[152:153] op_sel_hi:[1,0]
	v_pk_mul_f32 v[80:81], v[80:81], v[152:153] op_sel_hi:[1,0]
	v_pk_mul_f32 v[66:67], v[66:67], v[150:151] op_sel_hi:[1,0]
	v_pk_mul_f32 v[64:65], v[64:65], v[150:151] op_sel_hi:[1,0]
	v_pk_mul_f32 v[86:87], v[86:87], v[152:153] op_sel_hi:[1,0]
	v_pk_mul_f32 v[84:85], v[84:85], v[152:153] op_sel_hi:[1,0]
	v_pk_mul_f32 v[78:79], v[78:79], v[150:151] op_sel_hi:[1,0]
	v_pk_mul_f32 v[76:77], v[76:77], v[150:151] op_sel_hi:[1,0]
	v_pk_mul_f32 v[90:91], v[90:91], v[152:153] op_sel_hi:[1,0]
	v_pk_mul_f32 v[88:89], v[88:89], v[152:153] op_sel_hi:[1,0]
	v_pk_mul_f32 v[74:75], v[74:75], v[150:151] op_sel_hi:[1,0]
	v_pk_mul_f32 v[72:73], v[72:73], v[150:151] op_sel_hi:[1,0]
	v_pk_mul_f32 v[70:71], v[70:71], v[150:151] op_sel_hi:[1,0]
	v_pk_mul_f32 v[68:69], v[68:69], v[150:151] op_sel_hi:[1,0]
	s_waitcnt vmcnt(0)
	v_pk_mul_f32 v[94:95], v[14:15], v[126:127]
	v_pk_mul_f32 v[92:93], v[12:13], v[124:125]
	v_pk_mul_f32 v[98:99], v[10:11], v[122:123]
	v_pk_mul_f32 v[96:97], v[8:9], v[120:121]
	v_pk_mul_f32 v[102:103], v[6:7], v[118:119]
	v_pk_mul_f32 v[100:101], v[4:5], v[116:117]
	v_pk_mul_f32 v[106:107], v[2:3], v[114:115]
	v_pk_mul_f32 v[104:105], v[0:1], v[112:113]
	v_pk_mul_f32 v[110:111], v[14:15], v[110:111]
	v_pk_mul_f32 v[108:109], v[12:13], v[108:109]
	v_pk_mul_f32 v[114:115], v[10:11], v[166:167]
	v_pk_mul_f32 v[112:113], v[8:9], v[168:169]
	v_pk_mul_f32 v[118:119], v[6:7], v[170:171]
	v_pk_mul_f32 v[116:117], v[4:5], v[172:173]
	v_pk_mul_f32 v[122:123], v[2:3], v[176:177]
	v_pk_mul_f32 v[120:121], v[0:1], v[162:163]
	global_store_dwordx4 v[156:157], v[92:95], off
	global_store_dwordx4 v[156:157], v[96:99], off offset:16
	global_store_dwordx4 v[156:157], v[100:103], off offset:128
	global_store_dwordx4 v[156:157], v[104:107], off offset:144
	global_store_dwordx4 v[154:155], v[108:111], off
	global_store_dwordx4 v[154:155], v[112:115], off offset:16
	global_store_dwordx4 v[154:155], v[116:119], off offset:128
	global_store_dwordx4 v[154:155], v[120:123], off offset:144
	v_lshl_add_u64 v[92:93], s[62:63], 0, v[146:147]
	v_lshl_add_u64 v[92:93], v[92:93], 0, s[0:1]
	v_lshl_add_u64 v[92:93], v[92:93], 0, s[2:3]
	v_lshl_add_u64 v[92:93], v[92:93], 0, v[132:133]
	v_pk_mul_f32 v[82:83], v[2:3], v[82:83]
	v_pk_mul_f32 v[80:81], v[0:1], v[80:81]
	global_store_dwordx4 v[92:93], v[80:83], off offset:144
	v_pk_mul_f32 v[66:67], v[2:3], v[66:67]
	v_pk_mul_f32 v[64:65], v[0:1], v[64:65]
	v_add_u32_e32 v80, s16, v151
	v_ashrrev_i32_e32 v81, 31, v80
	v_lshlrev_b64 v[80:81], 12, v[80:81]
	v_lshl_add_u64 v[80:81], s[62:63], 0, v[80:81]
	v_lshl_add_u64 v[80:81], v[80:81], 0, s[0:1]
	v_lshl_add_u64 v[80:81], v[80:81], 0, s[2:3]
;     __device__ __forceinline__ void fused(f32x4 (&acc)[2][2][4][2], const Unit& u, int wr, int wc, int fr, int fq, PG8_LAS unsigned char* lds, int wid, int lane) const {
;     ...
; #pragma unroll
;         for (int ai = 0; ai < 2; ++ai)
; #pragma unroll
;             for (int m = 0; m < 4; ++m) {
;                 const int rl = ai * HALF + wr * 64 + m * 16 + fr; const size_t row = (size_t)(u.pm * BM + rl);
;                 const float rs = Sr[rl];
; #pragma unroll
;                 for (int bj = 0; bj < 2; ++bj)
; #pragma unroll
;                     for (int n = 0; n < 2; ++n)
;                         *(f32x4*)(y + row * DM + u.pn * BM + wc * 64 + bj * 32 + n * 4 + 8 * fq) = acc[ai][bj][m][n] * rs * nf[bj][n];
	v_lshl_add_u64 v[80:81], v[80:81], 0, v[132:133]
	global_store_dwordx4 v[80:81], v[64:67], off offset:144
	v_pk_mul_f32 v[86:87], v[6:7], v[86:87]
	v_pk_mul_f32 v[84:85], v[4:5], v[84:85]
	v_add_u32_e32 v64, s16, v153
	v_ashrrev_i32_e32 v65, 31, v64
	v_lshlrev_b64 v[64:65], 12, v[64:65]
	v_lshl_add_u64 v[64:65], s[62:63], 0, v[64:65]
	v_mov_b32_e32 v66, v149
	v_lshl_add_u64 v[64:65], v[64:65], 0, s[0:1]
	v_lshl_add_u64 v[64:65], v[64:65], 0, s[2:3]
	v_pk_mul_f32 v[54:55], v[54:55], v[66:67] op_sel_hi:[1,0]
	v_pk_mul_f32 v[52:53], v[52:53], v[66:67] op_sel_hi:[1,0]
	v_pk_mul_f32 v[50:51], v[50:51], v[66:67] op_sel_hi:[1,0]
	v_pk_mul_f32 v[48:49], v[48:49], v[66:67] op_sel_hi:[1,0]
	v_lshl_add_u64 v[64:65], v[64:65], 0, v[132:133]
	v_pk_mul_f32 v[54:55], v[6:7], v[54:55]
	v_pk_mul_f32 v[52:53], v[4:5], v[52:53]
	v_pk_mul_f32 v[50:51], v[2:3], v[50:51]
	v_pk_mul_f32 v[48:49], v[0:1], v[48:49]
	global_store_dwordx4 v[64:65], v[52:55], off offset:128
	ds_read2_b32 v[52:53], v161 offset0:144 offset1:160
	global_store_dwordx4 v[64:65], v[48:51], off offset:144
	global_store_dwordx4 v[92:93], v[84:87], off offset:128
	v_pk_mul_f32 v[62:63], v[62:63], v[66:67] op_sel_hi:[1,0]
	v_add_u32_e32 v48, s16, v158
	v_ashrrev_i32_e32 v49, 31, v48
	v_lshlrev_b64 v[48:49], 12, v[48:49]
	v_lshl_add_u64 v[48:49], s[62:63], 0, v[48:49]
	v_lshl_add_u64 v[48:49], v[48:49], 0, s[0:1]
	v_lshl_add_u64 v[48:49], v[48:49], 0, s[2:3]
	s_waitcnt lgkmcnt(0)
	v_pk_mul_f32 v[34:35], v[34:35], v[52:53] op_sel_hi:[1,0]
	v_pk_mul_f32 v[32:33], v[32:33], v[52:53] op_sel_hi:[1,0]
	v_lshl_add_u64 v[48:49], v[48:49], 0, v[132:133]
	v_pk_mul_f32 v[34:35], v[2:3], v[34:35]
	v_pk_mul_f32 v[32:33], v[0:1], v[32:33]
	global_store_dwordx4 v[48:49], v[32:35], off offset:144
	v_pk_mul_f32 v[60:61], v[60:61], v[66:67] op_sel_hi:[1,0]
	v_pk_mul_f32 v[46:47], v[46:47], v[52:53] op_sel_hi:[1,0]
	v_add_u32_e32 v32, s16, v159
	v_ashrrev_i32_e32 v33, 31, v32
	v_lshlrev_b64 v[32:33], 12, v[32:33]
	v_lshl_add_u64 v[32:33], s[62:63], 0, v[32:33]
	v_mov_b32_e32 v34, v53
	v_lshl_add_u64 v[32:33], v[32:33], 0, s[0:1]
	v_lshl_add_u64 v[32:33], v[32:33], 0, s[2:3]
	v_pk_mul_f32 v[18:19], v[18:19], v[34:35] op_sel_hi:[1,0]
	v_pk_mul_f32 v[16:17], v[16:17], v[34:35] op_sel_hi:[1,0]
	v_lshl_add_u64 v[32:33], v[32:33], 0, v[132:133]
	v_pk_mul_f32 v[18:19], v[2:3], v[18:19]
	v_pk_mul_f32 v[16:17], v[0:1], v[16:17]
	global_store_dwordx4 v[32:33], v[16:19], off offset:144
	v_pk_mul_f32 v[22:23], v[22:23], v[34:35] op_sel_hi:[1,0]
	v_pk_mul_f32 v[20:21], v[20:21], v[34:35] op_sel_hi:[1,0]
	v_add_u32_e32 v16, s16, v160
	v_ashrrev_i32_e32 v17, 31, v16
	v_lshlrev_b64 v[16:17], 12, v[16:17]
	v_lshl_add_u64 v[16:17], s[62:63], 0, v[16:17]
	v_pk_mul_f32 v[22:23], v[6:7], v[22:23]
	v_pk_mul_f32 v[20:21], v[4:5], v[20:21]
	v_lshl_add_u64 v[16:17], v[16:17], 0, s[0:1]
	v_pk_mul_f32 v[44:45], v[44:45], v[52:53] op_sel_hi:[1,0]
	v_pk_mul_f32 v[30:31], v[30:31], v[34:35] op_sel_hi:[1,0]
	v_pk_mul_f32 v[28:29], v[28:29], v[34:35] op_sel_hi:[1,0]
	global_store_dwordx4 v[32:33], v[20:23], off offset:128
	v_pk_mul_f32 v[18:19], v[134:135], v[164:165] op_sel_hi:[1,0]
	v_lshl_add_u64 v[16:17], v[16:17], 0, s[2:3]
	v_pk_mul_f32 v[20:21], v[136:137], v[164:165] op_sel_hi:[1,0]
	v_pk_mul_f32 v[126:127], v[14:15], v[178:179]
	v_pk_mul_f32 v[124:125], v[12:13], v[180:181]
	v_pk_mul_f32 v[78:79], v[14:15], v[78:79]
	v_pk_mul_f32 v[76:77], v[12:13], v[76:77]
	v_pk_mul_f32 v[62:63], v[14:15], v[62:63]
	v_pk_mul_f32 v[60:61], v[12:13], v[60:61]
	v_pk_mul_f32 v[46:47], v[14:15], v[46:47]
	v_pk_mul_f32 v[44:45], v[12:13], v[44:45]
	v_pk_mul_f32 v[30:31], v[14:15], v[30:31]
	v_pk_mul_f32 v[28:29], v[12:13], v[28:29]
	v_pk_mul_f32 v[14:15], v[14:15], v[18:19]
	v_pk_mul_f32 v[12:13], v[12:13], v[20:21]
	v_lshl_add_u64 v[16:17], v[16:17], 0, v[132:133]
	global_store_dwordx4 v[80:81], v[76:79], off
	v_pk_mul_f32 v[58:59], v[58:59], v[66:67] op_sel_hi:[1,0]
	v_pk_mul_f32 v[56:57], v[56:57], v[66:67] op_sel_hi:[1,0]
	v_pk_mul_f32 v[42:43], v[42:43], v[52:53] op_sel_hi:[1,0]
	v_pk_mul_f32 v[40:41], v[40:41], v[52:53] op_sel_hi:[1,0]
	v_pk_mul_f32 v[26:27], v[26:27], v[34:35] op_sel_hi:[1,0]
	v_pk_mul_f32 v[24:25], v[24:25], v[34:35] op_sel_hi:[1,0]
	global_store_dwordx4 v[16:17], v[12:15], off
	v_pk_mul_f32 v[90:91], v[10:11], v[90:91]
	v_pk_mul_f32 v[88:89], v[8:9], v[88:89]
	v_pk_mul_f32 v[12:13], v[128:129], v[164:165] op_sel_hi:[1,0]
	v_pk_mul_f32 v[14:15], v[130:131], v[164:165] op_sel_hi:[1,0]
	v_pk_mul_f32 v[74:75], v[10:11], v[74:75]
	v_pk_mul_f32 v[72:73], v[8:9], v[72:73]
	v_pk_mul_f32 v[58:59], v[10:11], v[58:59]
	v_pk_mul_f32 v[56:57], v[8:9], v[56:57]
	v_pk_mul_f32 v[42:43], v[10:11], v[42:43]
	v_pk_mul_f32 v[40:41], v[8:9], v[40:41]
	v_pk_mul_f32 v[26:27], v[10:11], v[26:27]
	v_pk_mul_f32 v[24:25], v[8:9], v[24:25]
	v_pk_mul_f32 v[10:11], v[10:11], v[12:13]
	v_pk_mul_f32 v[8:9], v[8:9], v[14:15]
	global_store_dwordx4 v[80:81], v[72:75], off offset:16
	v_pk_mul_f32 v[38:39], v[38:39], v[52:53] op_sel_hi:[1,0]
	v_pk_mul_f32 v[36:37], v[36:37], v[52:53] op_sel_hi:[1,0]
	global_store_dwordx4 v[16:17], v[8:11], off offset:16
	v_pk_mul_f32 v[70:71], v[6:7], v[70:71]
	v_pk_mul_f32 v[68:69], v[4:5], v[68:69]
	v_pk_mul_f32 v[8:9], v[138:139], v[164:165] op_sel_hi:[1,0]
	v_pk_mul_f32 v[10:11], v[142:143], v[164:165] op_sel_hi:[1,0]
	v_pk_mul_f32 v[38:39], v[6:7], v[38:39]
	v_pk_mul_f32 v[36:37], v[4:5], v[36:37]
	v_pk_mul_f32 v[6:7], v[6:7], v[8:9]
	v_pk_mul_f32 v[4:5], v[4:5], v[10:11]
	global_store_dwordx4 v[80:81], v[68:71], off offset:128
	global_store_dwordx4 v[16:17], v[4:7], off offset:128
	global_store_dwordx4 v[92:93], v[124:127], off
	global_store_dwordx4 v[92:93], v[88:91], off offset:16
	v_pk_mul_f32 v[4:5], v[140:141], v[164:165] op_sel_hi:[1,0]
	v_pk_mul_f32 v[6:7], v[144:145], v[164:165] op_sel_hi:[1,0]
	v_pk_mul_f32 v[2:3], v[2:3], v[4:5]
	v_pk_mul_f32 v[0:1], v[0:1], v[6:7]
	global_store_dwordx4 v[64:65], v[60:63], off
	global_store_dwordx4 v[64:65], v[56:59], off offset:16
	global_store_dwordx4 v[48:49], v[44:47], off
	global_store_dwordx4 v[48:49], v[40:43], off offset:16
	global_store_dwordx4 v[48:49], v[36:39], off offset:128
	global_store_dwordx4 v[32:33], v[28:31], off
	global_store_dwordx4 v[32:33], v[24:27], off offset:16
	global_store_dwordx4 v[16:17], v[0:3], off offset:144
